# own scan block B3 (rotating coalesced loader, scaled recurrence, trickled LDS writes, loads issued in idle window) + XCD-affine hg_seq map + hg_seq prefetch wait fix
# speedup vs baseline: 1.0075x; 1.0075x over previous
; #define LAS __attribute__((address_space(3)))
; __device__ __forceinline__ void rwkv_scan(const Params& p, LAS unsigned char* lds, int rowbase, int T, int h, int q4, const float* S0, float* Sout) {
;     ...
;         if (ldr) {
; #pragma unroll
;             for (int q = 0; q < 2; ++q) {
;                 const int st_ = lstep + q * 16;
;                 *(LAS f32x4*)(b + st_ * 256 + lj * 16) = gd[q];
;                 *(LAS f32x4*)(b + 8192 + st_ * 256 + lj * 16) = up4(gk[q]);
;                 *(LAS f32x4*)(b + 16384 + st_ * 256 + lj * 16) = up4(ga[q]);
;                 *(LAS f32x4*)(b + 24576 + st_ * 256 + lj * 16) = up4(gp[q]);
;                 *(LAS f32x4*)(b + 32768 + st_ * 256 + lj * 16) = up4(gr[q]);
;                 if (lj < 4) *(LAS f32x4*)(b + 40960 + st_ * 64 + lj * 16) = up4(gv[q]);
;             }
;         }
.Lrw3_nb3:
	s_add_i32 s50, s50, 1
	v_lshlrev_b32_e32 v6, 16, v72
	v_and_b32_e32 v7, 0xffff0000, v72
	v_lshlrev_b32_e32 v8, 16, v73
	v_and_b32_e32 v9, 0xffff0000, v73
	v_mul_f32_e32 v202, v6, v184
	v_mul_f32_e32 v203, v7, v185
	v_mul_f32_e32 v204, v8, v186
	v_mul_f32_e32 v205, v9, v187
	v_lshlrev_b32_e32 v10, 16, v88
	v_and_b32_e32 v11, 0xffff0000, v88
	v_lshlrev_b32_e32 v12, 16, v89
	v_and_b32_e32 v13, 0xffff0000, v89
	v_mul_f32_e32 v206, v10, v152
	v_mul_f32_e32 v207, v11, v153
	v_mul_f32_e32 v208, v12, v154
	v_mul_f32_e32 v209, v13, v155
	v_lshlrev_b32_e32 v6, 16, v104
	v_and_b32_e32 v7, 0xffff0000, v104
	v_lshlrev_b32_e32 v8, 16, v105
	v_and_b32_e32 v9, 0xffff0000, v105
	v_mul_f32_e32 v210, v6, v152
	v_mul_f32_e32 v211, v7, v153
	v_mul_f32_e32 v212, v8, v154
	v_mul_f32_e32 v213, v9, v155
	v_lshlrev_b32_e32 v10, 16, v120
	v_and_b32_e32 v11, 0xffff0000, v120
	v_lshlrev_b32_e32 v12, 16, v121
	v_and_b32_e32 v13, 0xffff0000, v121
	v_mul_f32_e32 v214, v10, v40
	v_mul_f32_e32 v215, v11, v41
	v_mul_f32_e32 v216, v12, v42
	v_mul_f32_e32 v217, v13, v43
	s_sleep 1
	ds_write_b128 v32, v[202:205] offset:0
	ds_write_b128 v32, v[206:209] offset:8192
	ds_write_b128 v32, v[210:213] offset:16384
	ds_write_b128 v32, v[214:217] offset:24576
	v_lshlrev_b32_e32 v6, 16, v74
	v_and_b32_e32 v7, 0xffff0000, v74
	v_lshlrev_b32_e32 v8, 16, v75
	v_and_b32_e32 v9, 0xffff0000, v75
	v_mul_f32_e32 v218, v6, v40
	v_mul_f32_e32 v219, v7, v41
	v_mul_f32_e32 v220, v8, v42
	v_mul_f32_e32 v221, v9, v43
	v_lshlrev_b32_e32 v10, 16, v90
	v_and_b32_e32 v11, 0xffff0000, v90
	v_lshlrev_b32_e32 v12, 16, v91
	v_and_b32_e32 v13, 0xffff0000, v91
	v_mul_f32_e32 v222, v10, v156
	v_mul_f32_e32 v223, v11, v157
	v_mul_f32_e32 v224, v12, v158
	v_mul_f32_e32 v225, v13, v159
	v_lshlrev_b32_e32 v6, 16, v106
	v_and_b32_e32 v7, 0xffff0000, v106
	v_lshlrev_b32_e32 v8, 16, v107
	v_and_b32_e32 v9, 0xffff0000, v107
	v_mul_f32_e32 v226, v6, v156
	v_mul_f32_e32 v227, v7, v157
	v_mul_f32_e32 v228, v8, v158
	v_mul_f32_e32 v229, v9, v159
	v_lshlrev_b32_e32 v10, 16, v122
	v_and_b32_e32 v11, 0xffff0000, v122
	v_lshlrev_b32_e32 v12, 16, v123
	v_and_b32_e32 v13, 0xffff0000, v123
	v_mul_f32_e32 v230, v10, v44
	v_mul_f32_e32 v231, v11, v45
	v_mul_f32_e32 v232, v12, v46
	v_mul_f32_e32 v233, v13, v47
	s_sleep 1
	ds_write_b128 v32, v[218:221] offset:256
	ds_write_b128 v32, v[222:225] offset:8448
	ds_write_b128 v32, v[226:229] offset:16640
	ds_write_b128 v32, v[230:233] offset:24832
	s_waitcnt lgkmcnt(4)
	v_lshlrev_b32_e32 v6, 16, v76
	v_and_b32_e32 v7, 0xffff0000, v76
	v_lshlrev_b32_e32 v8, 16, v77
	v_and_b32_e32 v9, 0xffff0000, v77
	v_mul_f32_e32 v202, v6, v44
	v_mul_f32_e32 v203, v7, v45
	v_mul_f32_e32 v204, v8, v46
	v_mul_f32_e32 v205, v9, v47
	v_lshlrev_b32_e32 v10, 16, v92
	v_and_b32_e32 v11, 0xffff0000, v92
	v_lshlrev_b32_e32 v12, 16, v93
	v_and_b32_e32 v13, 0xffff0000, v93
	v_mul_f32_e32 v206, v10, v160
	v_mul_f32_e32 v207, v11, v161
	v_mul_f32_e32 v208, v12, v162
	v_mul_f32_e32 v209, v13, v163
	v_lshlrev_b32_e32 v6, 16, v108
	v_and_b32_e32 v7, 0xffff0000, v108
	v_lshlrev_b32_e32 v8, 16, v109
	v_and_b32_e32 v9, 0xffff0000, v109
	v_mul_f32_e32 v210, v6, v160
	v_mul_f32_e32 v211, v7, v161
	v_mul_f32_e32 v212, v8, v162
	v_mul_f32_e32 v213, v9, v163
	v_lshlrev_b32_e32 v10, 16, v124
	v_and_b32_e32 v11, 0xffff0000, v124
	v_lshlrev_b32_e32 v12, 16, v125
	v_and_b32_e32 v13, 0xffff0000, v125
	v_mul_f32_e32 v214, v10, v48
	v_mul_f32_e32 v215, v11, v49
	v_mul_f32_e32 v216, v12, v50
	v_mul_f32_e32 v217, v13, v51
	s_sleep 1
	ds_write_b128 v32, v[202:205] offset:512
	ds_write_b128 v32, v[206:209] offset:8704
	ds_write_b128 v32, v[210:213] offset:16896
	ds_write_b128 v32, v[214:217] offset:25088
	s_waitcnt lgkmcnt(4)
	v_lshlrev_b32_e32 v6, 16, v78
	v_and_b32_e32 v7, 0xffff0000, v78
	v_lshlrev_b32_e32 v8, 16, v79
	v_and_b32_e32 v9, 0xffff0000, v79
	v_mul_f32_e32 v218, v6, v48
	v_mul_f32_e32 v219, v7, v49
	v_mul_f32_e32 v220, v8, v50
	v_mul_f32_e32 v221, v9, v51
	v_lshlrev_b32_e32 v10, 16, v94
	v_and_b32_e32 v11, 0xffff0000, v94
	v_lshlrev_b32_e32 v12, 16, v95
	v_and_b32_e32 v13, 0xffff0000, v95
	v_mul_f32_e32 v222, v10, v164
	v_mul_f32_e32 v223, v11, v165
	v_mul_f32_e32 v224, v12, v166
	v_mul_f32_e32 v225, v13, v167
	v_lshlrev_b32_e32 v6, 16, v110
	v_and_b32_e32 v7, 0xffff0000, v110
	v_lshlrev_b32_e32 v8, 16, v111
	v_and_b32_e32 v9, 0xffff0000, v111
	v_mul_f32_e32 v226, v6, v164
	v_mul_f32_e32 v227, v7, v165
	v_mul_f32_e32 v228, v8, v166
	v_mul_f32_e32 v229, v9, v167
	v_lshlrev_b32_e32 v10, 16, v126
	v_and_b32_e32 v11, 0xffff0000, v126
	v_lshlrev_b32_e32 v12, 16, v127
	v_and_b32_e32 v13, 0xffff0000, v127
	v_mul_f32_e32 v230, v10, v52
	v_mul_f32_e32 v231, v11, v53
	v_mul_f32_e32 v232, v12, v54
	v_mul_f32_e32 v233, v13, v55
	s_sleep 1
	ds_write_b128 v32, v[218:221] offset:768
	ds_write_b128 v32, v[222:225] offset:8960
	ds_write_b128 v32, v[226:229] offset:17152
	ds_write_b128 v32, v[230:233] offset:25344
	s_waitcnt lgkmcnt(4)
	v_lshlrev_b32_e32 v6, 16, v80
	v_and_b32_e32 v7, 0xffff0000, v80
	v_lshlrev_b32_e32 v8, 16, v81
	v_and_b32_e32 v9, 0xffff0000, v81
	v_mul_f32_e32 v202, v6, v52
	v_mul_f32_e32 v203, v7, v53
	v_mul_f32_e32 v204, v8, v54
	v_mul_f32_e32 v205, v9, v55
	v_lshlrev_b32_e32 v10, 16, v96
	v_and_b32_e32 v11, 0xffff0000, v96
	v_lshlrev_b32_e32 v12, 16, v97
	v_and_b32_e32 v13, 0xffff0000, v97
	v_mul_f32_e32 v206, v10, v168
	v_mul_f32_e32 v207, v11, v169
	v_mul_f32_e32 v208, v12, v170
	v_mul_f32_e32 v209, v13, v171
	v_lshlrev_b32_e32 v6, 16, v112
	v_and_b32_e32 v7, 0xffff0000, v112
	v_lshlrev_b32_e32 v8, 16, v113
	v_and_b32_e32 v9, 0xffff0000, v113
	v_mul_f32_e32 v210, v6, v168
	v_mul_f32_e32 v211, v7, v169
	v_mul_f32_e32 v212, v8, v170
	v_mul_f32_e32 v213, v9, v171
	v_lshlrev_b32_e32 v10, 16, v128
	v_and_b32_e32 v11, 0xffff0000, v128
	v_lshlrev_b32_e32 v12, 16, v129
	v_and_b32_e32 v13, 0xffff0000, v129
	v_mul_f32_e32 v214, v10, v56
	v_mul_f32_e32 v215, v11, v57
	v_mul_f32_e32 v216, v12, v58
	v_mul_f32_e32 v217, v13, v59
	s_sleep 1
	ds_write_b128 v32, v[202:205] offset:1024
	ds_write_b128 v32, v[206:209] offset:9216
	ds_write_b128 v32, v[210:213] offset:17408
	ds_write_b128 v32, v[214:217] offset:25600
	s_waitcnt lgkmcnt(4)
; #define LAS __attribute__((address_space(3)))
; __device__ __forceinline__ void rwkv_scan(const Params& p, LAS unsigned char* lds, int rowbase, int T, int h, int q4, const float* S0, float* Sout) {
;     ...
;         if (ldr) {
; #pragma unroll
;             for (int q = 0; q < 2; ++q) {
;                 const int st_ = lstep + q * 16;
;                 *(LAS f32x4*)(b + st_ * 256 + lj * 16) = gd[q];
;                 *(LAS f32x4*)(b + 8192 + st_ * 256 + lj * 16) = up4(gk[q]);
;                 *(LAS f32x4*)(b + 16384 + st_ * 256 + lj * 16) = up4(ga[q]);
;                 *(LAS f32x4*)(b + 24576 + st_ * 256 + lj * 16) = up4(gp[q]);
;                 *(LAS f32x4*)(b + 32768 + st_ * 256 + lj * 16) = up4(gr[q]);
;                 if (lj < 4) *(LAS f32x4*)(b + 40960 + st_ * 64 + lj * 16) = up4(gv[q]);
;             }
;         }
;         __syncthreads();
;         if (c + 1 < nch) gload(c + 1);
	v_lshlrev_b32_e32 v6, 16, v82
	v_and_b32_e32 v7, 0xffff0000, v82
	v_lshlrev_b32_e32 v8, 16, v83
	v_and_b32_e32 v9, 0xffff0000, v83
	v_mul_f32_e32 v218, v6, v56
	v_mul_f32_e32 v219, v7, v57
	v_mul_f32_e32 v220, v8, v58
	v_mul_f32_e32 v221, v9, v59
	v_lshlrev_b32_e32 v10, 16, v98
	v_and_b32_e32 v11, 0xffff0000, v98
	v_lshlrev_b32_e32 v12, 16, v99
	v_and_b32_e32 v13, 0xffff0000, v99
	v_mul_f32_e32 v222, v10, v172
	v_mul_f32_e32 v223, v11, v173
	v_mul_f32_e32 v224, v12, v174
	v_mul_f32_e32 v225, v13, v175
	v_lshlrev_b32_e32 v6, 16, v114
	v_and_b32_e32 v7, 0xffff0000, v114
	v_lshlrev_b32_e32 v8, 16, v115
	v_and_b32_e32 v9, 0xffff0000, v115
	v_mul_f32_e32 v226, v6, v172
	v_mul_f32_e32 v227, v7, v173
	v_mul_f32_e32 v228, v8, v174
	v_mul_f32_e32 v229, v9, v175
	v_lshlrev_b32_e32 v10, 16, v130
	v_and_b32_e32 v11, 0xffff0000, v130
	v_lshlrev_b32_e32 v12, 16, v131
	v_and_b32_e32 v13, 0xffff0000, v131
	v_mul_f32_e32 v230, v10, v60
	v_mul_f32_e32 v231, v11, v61
	v_mul_f32_e32 v232, v12, v62
	v_mul_f32_e32 v233, v13, v63
	s_sleep 1
	ds_write_b128 v32, v[218:221] offset:1280
	ds_write_b128 v32, v[222:225] offset:9472
	ds_write_b128 v32, v[226:229] offset:17664
	ds_write_b128 v32, v[230:233] offset:25856
	s_waitcnt lgkmcnt(4)
	v_lshlrev_b32_e32 v6, 16, v84
	v_and_b32_e32 v7, 0xffff0000, v84
	v_lshlrev_b32_e32 v8, 16, v85
	v_and_b32_e32 v9, 0xffff0000, v85
	v_mul_f32_e32 v202, v6, v60
	v_mul_f32_e32 v203, v7, v61
	v_mul_f32_e32 v204, v8, v62
	v_mul_f32_e32 v205, v9, v63
	v_lshlrev_b32_e32 v10, 16, v100
	v_and_b32_e32 v11, 0xffff0000, v100
	v_lshlrev_b32_e32 v12, 16, v101
	v_and_b32_e32 v13, 0xffff0000, v101
	v_mul_f32_e32 v206, v10, v176
	v_mul_f32_e32 v207, v11, v177
	v_mul_f32_e32 v208, v12, v178
	v_mul_f32_e32 v209, v13, v179
	v_lshlrev_b32_e32 v6, 16, v116
	v_and_b32_e32 v7, 0xffff0000, v116
	v_lshlrev_b32_e32 v8, 16, v117
	v_and_b32_e32 v9, 0xffff0000, v117
	v_mul_f32_e32 v210, v6, v176
	v_mul_f32_e32 v211, v7, v177
	v_mul_f32_e32 v212, v8, v178
	v_mul_f32_e32 v213, v9, v179
	v_lshlrev_b32_e32 v10, 16, v132
	v_and_b32_e32 v11, 0xffff0000, v132
	v_lshlrev_b32_e32 v12, 16, v133
	v_and_b32_e32 v13, 0xffff0000, v133
	v_mul_f32_e32 v214, v10, v64
	v_mul_f32_e32 v215, v11, v65
	v_mul_f32_e32 v216, v12, v66
	v_mul_f32_e32 v217, v13, v67
	s_sleep 1
	ds_write_b128 v32, v[202:205] offset:1536
	ds_write_b128 v32, v[206:209] offset:9728
	ds_write_b128 v32, v[210:213] offset:17920
	ds_write_b128 v32, v[214:217] offset:26112
	s_waitcnt lgkmcnt(4)
	v_lshlrev_b32_e32 v6, 16, v86
	v_and_b32_e32 v7, 0xffff0000, v86
	v_lshlrev_b32_e32 v8, 16, v87
	v_and_b32_e32 v9, 0xffff0000, v87
	v_mul_f32_e32 v218, v6, v64
	v_mul_f32_e32 v219, v7, v65
	v_mul_f32_e32 v220, v8, v66
	v_mul_f32_e32 v221, v9, v67
	v_lshlrev_b32_e32 v10, 16, v102
	v_and_b32_e32 v11, 0xffff0000, v102
	v_lshlrev_b32_e32 v12, 16, v103
	v_and_b32_e32 v13, 0xffff0000, v103
	v_mul_f32_e32 v222, v10, v180
	v_mul_f32_e32 v223, v11, v181
	v_mul_f32_e32 v224, v12, v182
	v_mul_f32_e32 v225, v13, v183
	v_lshlrev_b32_e32 v6, 16, v118
	v_and_b32_e32 v7, 0xffff0000, v118
	v_lshlrev_b32_e32 v8, 16, v119
	v_and_b32_e32 v9, 0xffff0000, v119
	v_mul_f32_e32 v226, v6, v180
	v_mul_f32_e32 v227, v7, v181
	v_mul_f32_e32 v228, v8, v182
	v_mul_f32_e32 v229, v9, v183
	v_lshlrev_b32_e32 v10, 16, v134
	v_and_b32_e32 v11, 0xffff0000, v134
	v_lshlrev_b32_e32 v12, 16, v135
	v_and_b32_e32 v13, 0xffff0000, v135
	v_mul_f32_e32 v230, v10, v68
	v_mul_f32_e32 v231, v11, v69
	v_mul_f32_e32 v232, v12, v70
	v_mul_f32_e32 v233, v13, v71
	s_sleep 1
	ds_write_b128 v32, v[218:221] offset:1792
	ds_write_b128 v32, v[222:225] offset:9984
	ds_write_b128 v32, v[226:229] offset:18176
	ds_write_b128 v32, v[230:233] offset:26368
	s_mov_b64 exec, s[52:53]
	ds_write_b128 v34, v[68:71]
	s_mov_b64 exec, -1
	s_waitcnt lgkmcnt(0)
	v_lshlrev_b32_e32 v202, 16, v136
	v_and_b32_e32 v210, 0xffff0000, v136
	v_lshlrev_b32_e32 v218, 16, v137
	v_and_b32_e32 v226, 0xffff0000, v137
	v_lshlrev_b32_e32 v203, 16, v138
	v_and_b32_e32 v211, 0xffff0000, v138
	v_lshlrev_b32_e32 v219, 16, v139
	v_and_b32_e32 v227, 0xffff0000, v139
	v_lshlrev_b32_e32 v204, 16, v140
	v_and_b32_e32 v212, 0xffff0000, v140
	v_lshlrev_b32_e32 v220, 16, v141
	v_and_b32_e32 v228, 0xffff0000, v141
	v_lshlrev_b32_e32 v205, 16, v142
	v_and_b32_e32 v213, 0xffff0000, v142
	v_lshlrev_b32_e32 v221, 16, v143
	v_and_b32_e32 v229, 0xffff0000, v143
	v_lshlrev_b32_e32 v206, 16, v144
	v_and_b32_e32 v214, 0xffff0000, v144
	v_lshlrev_b32_e32 v222, 16, v145
	v_and_b32_e32 v230, 0xffff0000, v145
	v_lshlrev_b32_e32 v207, 16, v146
	v_and_b32_e32 v215, 0xffff0000, v146
	v_lshlrev_b32_e32 v223, 16, v147
	v_and_b32_e32 v231, 0xffff0000, v147
	v_lshlrev_b32_e32 v208, 16, v148
	v_and_b32_e32 v216, 0xffff0000, v148
	v_lshlrev_b32_e32 v224, 16, v149
	v_and_b32_e32 v232, 0xffff0000, v149
	v_lshlrev_b32_e32 v209, 16, v150
	v_and_b32_e32 v217, 0xffff0000, v150
	v_lshlrev_b32_e32 v225, 16, v151
	v_and_b32_e32 v233, 0xffff0000, v151
	s_mov_b64 exec, s[30:31]
	ds_write_b128 v33, v[202:205] offset:0
	ds_write_b128 v33, v[206:209] offset:16
	ds_write_b128 v33, v[210:213] offset:144
	ds_write_b128 v33, v[214:217] offset:160
	ds_write_b128 v33, v[218:221] offset:288
	ds_write_b128 v33, v[222:225] offset:304
	ds_write_b128 v33, v[226:229] offset:432
	ds_write_b128 v33, v[230:233] offset:448
	s_mov_b64 exec, -1
	s_waitcnt lgkmcnt(0)
	s_cmp_lt_u32 s50, 128
	s_cbranch_scc0 .Lrw3_nb4
	s_barrier
